# v38_strip
# baseline (speedup 1.0000x reference)
; __device__ __forceinline__ f32x4 mfma16(bf16x8 a, bf16x8 b, f32x4 c) { return __builtin_amdgcn_mfma_f32_16x16x32_bf16(a, b, c, 0, 0, 0); }
; template <int MM, int NN>
; __device__ __forceinline__ void gemm_tile_big(const bf16_t* __restrict__ Ab, int lda, const bf16_t* __restrict__ Bb, int ldb,
;                                               int K, char* shm, f32x4 (&acc)[MM][NN]) {
;     ...
;     for (int ks = 0; ks < 2; ++ks) {
;       bf16x8 At[MM], Bf[NN];
; #pragma unroll
;       for (int m = 0; m < MM; ++m) At[m] = *(const bf16x8*)(sA + lds_byte2(wr * (16 * MM) + m * 16 + fr, ks * 32 + fq * 8));
; #pragma unroll
;       for (int n = 0; n < NN; ++n) Bf[n] = *(const bf16x8*)(sB + lds_byte2(wc * (16 * NN) + n * 16 + fr, ks * 32 + fq * 8));
; #pragma unroll
;       for (int m = 0; m < MM; ++m)
; #pragma unroll
;         for (int n = 0; n < NN; ++n) acc[m][n] = mfma16(At[m], Bf[n], acc[m][n]);
; __device__ __forceinline__ void p6_gemm2(const Params& p, int layer, char* shm) {
;     ...
;   for (int task = blockIdx.x; task < 256; task += gridDim.x) {
;     const int jn = task >> 4, q = task & 15;
;     f32x4 acc[2][4];
;     gemm_tile_big<2, 4>(WSB(Ybf) + (size_t)STRIP0 * DM + q * 256, DM, WSB(WtOut) + ((size_t)layer * DM + jn * 256) * DM + q * 256, DM, 256, shm, acc);
.LBB0_1554:
	s_barrier
	v_and_b32_e32 v3, 15, v135
	v_bfe_u32 v4, v135, 4, 2
	v_lshrrev_b32_e32 v5, 6, v135
	v_lshlrev_b32_e32 v18, 10, v5
	v_lshl_add_u32 v18, v4, 4, v18
	v_mov_b32_e32 v19, 0
	v_lshl_add_u32 v6, v3, 13, v18
	v_mov_b32_e32 v7, 0
	v_lshl_add_u64 v[8:9], s[50:51], 0, v[6:7]
	s_mov_b32 s4, 0x20000
	s_mov_b32 s5, 0
	v_lshl_add_u64 v[10:11], v[8:9], 0, s[4:5]
	v_lshl_add_u64 v[12:13], v[10:11], 0, s[4:5]
	v_lshl_add_u64 v[14:15], v[12:13], 0, s[4:5]
	s_lshl_b32 s6, s10, 4
	s_add_i32 s6, s6, s14
	v_add_u32_e32 v16, s6, v3
	v_mov_b32_e32 v17, 0
	v_lshlrev_b64 v[16:17], 13, v[16:17]
	v_lshl_add_u64 v[16:17], s[46:47], 0, v[16:17]
	v_lshl_add_u64 v[16:17], v[16:17], 0, v[18:19]
	v_mov_b32_e32 v142, 0
	v_mov_b32_e32 v143, 0
	v_mov_b32_e32 v144, 0
	v_mov_b32_e32 v145, 0
	v_mov_b32_e32 v146, 0
	v_mov_b32_e32 v147, 0
	v_mov_b32_e32 v148, 0
	v_mov_b32_e32 v149, 0
	v_mov_b32_e32 v150, 0
	v_mov_b32_e32 v151, 0
	v_mov_b32_e32 v152, 0
	v_mov_b32_e32 v153, 0
	v_mov_b32_e32 v126, 0
	v_mov_b32_e32 v127, 0
	v_mov_b32_e32 v128, 0
	v_mov_b32_e32 v129, 0
	global_load_dwordx4 v[168:171], v[8:9], off
	global_load_dwordx4 v[172:175], v[10:11], off
	global_load_dwordx4 v[176:179], v[12:13], off
	global_load_dwordx4 v[180:183], v[14:15], off
	global_load_dwordx4 v[184:187], v[16:17], off
	global_load_dwordx4 v[188:191], v[8:9], off offset:64
	global_load_dwordx4 v[192:195], v[10:11], off offset:64
	global_load_dwordx4 v[196:199], v[12:13], off offset:64
	global_load_dwordx4 v[200:203], v[14:15], off offset:64
	global_load_dwordx4 v[204:207], v[16:17], off offset:64
	global_load_dwordx4 v[208:211], v[8:9], off offset:128
	global_load_dwordx4 v[212:215], v[10:11], off offset:128
	global_load_dwordx4 v[216:219], v[12:13], off offset:128
	global_load_dwordx4 v[220:223], v[14:15], off offset:128
	global_load_dwordx4 v[224:227], v[16:17], off offset:128
	global_load_dwordx4 v[228:231], v[8:9], off offset:192
	global_load_dwordx4 v[232:235], v[10:11], off offset:192
	global_load_dwordx4 v[236:239], v[12:13], off offset:192
	global_load_dwordx4 v[240:243], v[14:15], off offset:192
	global_load_dwordx4 v[244:247], v[16:17], off offset:192
	global_load_dwordx4 v[20:23], v[8:9], off offset:256
	global_load_dwordx4 v[24:27], v[10:11], off offset:256
	global_load_dwordx4 v[28:31], v[12:13], off offset:256
	global_load_dwordx4 v[32:35], v[14:15], off offset:256
	global_load_dwordx4 v[36:39], v[16:17], off offset:256
	global_load_dwordx4 v[40:43], v[8:9], off offset:320
	global_load_dwordx4 v[58:61], v[10:11], off offset:320
	global_load_dwordx4 v[62:65], v[12:13], off offset:320
	global_load_dwordx4 v[66:69], v[14:15], off offset:320
	global_load_dwordx4 v[70:73], v[16:17], off offset:320
	global_load_dwordx4 v[74:77], v[8:9], off offset:384
	global_load_dwordx4 v[78:81], v[10:11], off offset:384
	global_load_dwordx4 v[82:85], v[12:13], off offset:384
	global_load_dwordx4 v[86:89], v[14:15], off offset:384
	global_load_dwordx4 v[102:105], v[16:17], off offset:384
	global_load_dwordx4 v[106:109], v[8:9], off offset:448
	global_load_dwordx4 v[110:113], v[10:11], off offset:448
	global_load_dwordx4 v[114:117], v[12:13], off offset:448
	global_load_dwordx4 v[118:121], v[14:15], off offset:448
	global_load_dwordx4 v[122:125], v[16:17], off offset:448
	s_waitcnt vmcnt(20)
	v_mfma_f32_16x16x32_bf16 v[142:145], v[168:171], v[184:187], v[142:145]
	v_mfma_f32_16x16x32_bf16 v[146:149], v[172:175], v[184:187], v[146:149]
	v_mfma_f32_16x16x32_bf16 v[150:153], v[176:179], v[184:187], v[150:153]
	v_mfma_f32_16x16x32_bf16 v[126:129], v[180:183], v[184:187], v[126:129]
	v_mfma_f32_16x16x32_bf16 v[142:145], v[188:191], v[204:207], v[142:145]
	v_mfma_f32_16x16x32_bf16 v[146:149], v[192:195], v[204:207], v[146:149]
	v_mfma_f32_16x16x32_bf16 v[150:153], v[196:199], v[204:207], v[150:153]
	v_mfma_f32_16x16x32_bf16 v[126:129], v[200:203], v[204:207], v[126:129]
	v_mfma_f32_16x16x32_bf16 v[142:145], v[208:211], v[224:227], v[142:145]
	v_mfma_f32_16x16x32_bf16 v[146:149], v[212:215], v[224:227], v[146:149]
	v_mfma_f32_16x16x32_bf16 v[150:153], v[216:219], v[224:227], v[150:153]
	v_mfma_f32_16x16x32_bf16 v[126:129], v[220:223], v[224:227], v[126:129]
	v_mfma_f32_16x16x32_bf16 v[142:145], v[228:231], v[244:247], v[142:145]
	v_mfma_f32_16x16x32_bf16 v[146:149], v[232:235], v[244:247], v[146:149]
	v_mfma_f32_16x16x32_bf16 v[150:153], v[236:239], v[244:247], v[150:153]
	v_mfma_f32_16x16x32_bf16 v[126:129], v[240:243], v[244:247], v[126:129]
	global_load_dwordx4 v[168:171], v[8:9], off offset:512
	global_load_dwordx4 v[172:175], v[10:11], off offset:512
	global_load_dwordx4 v[176:179], v[12:13], off offset:512
	global_load_dwordx4 v[180:183], v[14:15], off offset:512
	global_load_dwordx4 v[184:187], v[16:17], off offset:512
	global_load_dwordx4 v[188:191], v[8:9], off offset:576
	global_load_dwordx4 v[192:195], v[10:11], off offset:576
	global_load_dwordx4 v[196:199], v[12:13], off offset:576
	global_load_dwordx4 v[200:203], v[14:15], off offset:576
	global_load_dwordx4 v[204:207], v[16:17], off offset:576
	global_load_dwordx4 v[208:211], v[8:9], off offset:640
	global_load_dwordx4 v[212:215], v[10:11], off offset:640
	global_load_dwordx4 v[216:219], v[12:13], off offset:640
	global_load_dwordx4 v[220:223], v[14:15], off offset:640
	global_load_dwordx4 v[224:227], v[16:17], off offset:640
	global_load_dwordx4 v[228:231], v[8:9], off offset:704
	global_load_dwordx4 v[232:235], v[10:11], off offset:704
	global_load_dwordx4 v[236:239], v[12:13], off offset:704
	global_load_dwordx4 v[240:243], v[14:15], off offset:704
	global_load_dwordx4 v[244:247], v[16:17], off offset:704
	s_waitcnt vmcnt(20)
; __device__ __forceinline__ f32x4 mfma16(bf16x8 a, bf16x8 b, f32x4 c) { return __builtin_amdgcn_mfma_f32_16x16x32_bf16(a, b, c, 0, 0, 0); }
; #define EPI_IDS() const int e_tid = otid(), e_wid = e_tid >> 6, e_lane = e_tid & 63, wr = e_wid >> 2, wc = e_wid & 3, fr = e_lane & 15, fq = e_lane >> 4
; template <int MM, int NN>
; __device__ __forceinline__ void gemm_tile_big(const bf16_t* __restrict__ Ab, int lda, const bf16_t* __restrict__ Bb, int ldb,
;                                               int K, char* shm, f32x4 (&acc)[MM][NN]) {
;     ...
;     for (int ks = 0; ks < 2; ++ks) {
;       bf16x8 At[MM], Bf[NN];
; #pragma unroll
;       for (int m = 0; m < MM; ++m) At[m] = *(const bf16x8*)(sA + lds_byte2(wr * (16 * MM) + m * 16 + fr, ks * 32 + fq * 8));
; #pragma unroll
;       for (int n = 0; n < NN; ++n) Bf[n] = *(const bf16x8*)(sB + lds_byte2(wc * (16 * NN) + n * 16 + fr, ks * 32 + fq * 8));
; #pragma unroll
;       for (int m = 0; m < MM; ++m)
; #pragma unroll
;         for (int n = 0; n < NN; ++n) acc[m][n] = mfma16(At[m], Bf[n], acc[m][n]);
; __device__ __forceinline__ void p6_gemm2(const Params& p, int layer, char* shm) {
;     ...
;     EPI_IDS();
; #pragma unroll
;     for (int m = 0; m < 2; ++m)
; #pragma unroll
;       for (int n = 0; n < 4; ++n)
; #pragma unroll
;         for (int j = 0; j < 4; ++j) {
;           const int row = STRIP0 + wr * 32 + m * 16 + fq * 4 + j, col = jn * 256 + EPI_COL(n);
;           float* dstp;
;           if (layer == 1) { int b = row / L, t = row % L; dstp = p.out + ((size_t)(b * SEQ + t - NMETA)) * DM + col; }
;           else dstp = WSF(h) + (size_t)row * DM + col;
;           atomicAdd(dstp, acc[m][n][j]);
;         }
	v_mfma_f32_16x16x32_bf16 v[142:145], v[20:23], v[36:39], v[142:145]
	v_mfma_f32_16x16x32_bf16 v[146:149], v[24:27], v[36:39], v[146:149]
	v_mfma_f32_16x16x32_bf16 v[150:153], v[28:31], v[36:39], v[150:153]
	v_mfma_f32_16x16x32_bf16 v[126:129], v[32:35], v[36:39], v[126:129]
	v_mfma_f32_16x16x32_bf16 v[142:145], v[40:43], v[70:73], v[142:145]
	v_mfma_f32_16x16x32_bf16 v[146:149], v[58:61], v[70:73], v[146:149]
	v_mfma_f32_16x16x32_bf16 v[150:153], v[62:65], v[70:73], v[150:153]
	v_mfma_f32_16x16x32_bf16 v[126:129], v[66:69], v[70:73], v[126:129]
	v_mfma_f32_16x16x32_bf16 v[142:145], v[74:77], v[102:105], v[142:145]
	v_mfma_f32_16x16x32_bf16 v[146:149], v[78:81], v[102:105], v[146:149]
	v_mfma_f32_16x16x32_bf16 v[150:153], v[82:85], v[102:105], v[150:153]
	v_mfma_f32_16x16x32_bf16 v[126:129], v[86:89], v[102:105], v[126:129]
	v_mfma_f32_16x16x32_bf16 v[142:145], v[106:109], v[122:125], v[142:145]
	v_mfma_f32_16x16x32_bf16 v[146:149], v[110:113], v[122:125], v[146:149]
	v_mfma_f32_16x16x32_bf16 v[150:153], v[114:117], v[122:125], v[150:153]
	v_mfma_f32_16x16x32_bf16 v[126:129], v[118:121], v[122:125], v[126:129]
	global_load_dwordx4 v[20:23], v[8:9], off offset:768
	global_load_dwordx4 v[24:27], v[10:11], off offset:768
	global_load_dwordx4 v[28:31], v[12:13], off offset:768
	global_load_dwordx4 v[32:35], v[14:15], off offset:768
	global_load_dwordx4 v[36:39], v[16:17], off offset:768
	global_load_dwordx4 v[40:43], v[8:9], off offset:832
	global_load_dwordx4 v[58:61], v[10:11], off offset:832
	global_load_dwordx4 v[62:65], v[12:13], off offset:832
	global_load_dwordx4 v[66:69], v[14:15], off offset:832
	global_load_dwordx4 v[70:73], v[16:17], off offset:832
	global_load_dwordx4 v[74:77], v[8:9], off offset:896
	global_load_dwordx4 v[78:81], v[10:11], off offset:896
	global_load_dwordx4 v[82:85], v[12:13], off offset:896
	global_load_dwordx4 v[86:89], v[14:15], off offset:896
	global_load_dwordx4 v[102:105], v[16:17], off offset:896
	global_load_dwordx4 v[106:109], v[8:9], off offset:960
	global_load_dwordx4 v[110:113], v[10:11], off offset:960
	global_load_dwordx4 v[114:117], v[12:13], off offset:960
	global_load_dwordx4 v[118:121], v[14:15], off offset:960
	global_load_dwordx4 v[122:125], v[16:17], off offset:960
	s_waitcnt vmcnt(20)
	v_mfma_f32_16x16x32_bf16 v[142:145], v[168:171], v[184:187], v[142:145]
	v_mfma_f32_16x16x32_bf16 v[146:149], v[172:175], v[184:187], v[146:149]
	v_mfma_f32_16x16x32_bf16 v[150:153], v[176:179], v[184:187], v[150:153]
	v_mfma_f32_16x16x32_bf16 v[126:129], v[180:183], v[184:187], v[126:129]
	v_mfma_f32_16x16x32_bf16 v[142:145], v[188:191], v[204:207], v[142:145]
	v_mfma_f32_16x16x32_bf16 v[146:149], v[192:195], v[204:207], v[146:149]
	v_mfma_f32_16x16x32_bf16 v[150:153], v[196:199], v[204:207], v[150:153]
	v_mfma_f32_16x16x32_bf16 v[126:129], v[200:203], v[204:207], v[126:129]
	v_mfma_f32_16x16x32_bf16 v[142:145], v[208:211], v[224:227], v[142:145]
	v_mfma_f32_16x16x32_bf16 v[146:149], v[212:215], v[224:227], v[146:149]
	v_mfma_f32_16x16x32_bf16 v[150:153], v[216:219], v[224:227], v[150:153]
	v_mfma_f32_16x16x32_bf16 v[126:129], v[220:223], v[224:227], v[126:129]
	v_mfma_f32_16x16x32_bf16 v[142:145], v[228:231], v[244:247], v[142:145]
	v_mfma_f32_16x16x32_bf16 v[146:149], v[232:235], v[244:247], v[146:149]
	v_mfma_f32_16x16x32_bf16 v[150:153], v[236:239], v[244:247], v[150:153]
	v_mfma_f32_16x16x32_bf16 v[126:129], v[240:243], v[244:247], v[126:129]
	s_waitcnt vmcnt(0)
	v_mfma_f32_16x16x32_bf16 v[142:145], v[20:23], v[36:39], v[142:145]
	v_mfma_f32_16x16x32_bf16 v[146:149], v[24:27], v[36:39], v[146:149]
	v_mfma_f32_16x16x32_bf16 v[150:153], v[28:31], v[36:39], v[150:153]
	v_mfma_f32_16x16x32_bf16 v[126:129], v[32:35], v[36:39], v[126:129]
	v_mfma_f32_16x16x32_bf16 v[142:145], v[40:43], v[70:73], v[142:145]
	v_mfma_f32_16x16x32_bf16 v[146:149], v[58:61], v[70:73], v[146:149]
	v_mfma_f32_16x16x32_bf16 v[150:153], v[62:65], v[70:73], v[150:153]
	v_mfma_f32_16x16x32_bf16 v[126:129], v[66:69], v[70:73], v[126:129]
	v_mfma_f32_16x16x32_bf16 v[142:145], v[74:77], v[102:105], v[142:145]
	v_mfma_f32_16x16x32_bf16 v[146:149], v[78:81], v[102:105], v[146:149]
	v_mfma_f32_16x16x32_bf16 v[150:153], v[82:85], v[102:105], v[150:153]
	v_mfma_f32_16x16x32_bf16 v[126:129], v[86:89], v[102:105], v[126:129]
	v_mfma_f32_16x16x32_bf16 v[142:145], v[106:109], v[122:125], v[142:145]
	v_mfma_f32_16x16x32_bf16 v[146:149], v[110:113], v[122:125], v[146:149]
	v_mfma_f32_16x16x32_bf16 v[150:153], v[114:117], v[122:125], v[150:153]
	v_mfma_f32_16x16x32_bf16 v[126:129], v[118:121], v[122:125], v[126:129]
	s_nop 7
	s_nop 7
	s_nop 7
	v_and_b32_e32 v6, 63, v135
	v_lshlrev_b32_e32 v6, 4, v6
	v_lshl_add_u32 v6, v5, 12, v6
	ds_write_b128 v6, v[142:145]
	ds_write_b128 v6, v[146:149] offset:1024
	ds_write_b128 v6, v[150:153] offset:2048
	ds_write_b128 v6, v[126:129] offset:3072
	s_waitcnt lgkmcnt(0)
	s_barrier
	v_lshrrev_b32_e32 v20, 7, v135
	v_bfe_u32 v21, v135, 1, 6
	v_and_b32_e32 v22, 1, v135
	v_lshlrev_b32_e32 v23, 10, v20
	v_lshl_add_u32 v23, v21, 4, v23
	v_lshl_add_u32 v23, v22, 3, v23
	ds_read_b64 v[58:59], v23
	ds_read_b64 v[60:61], v23 offset:4096
	ds_read_b64 v[62:63], v23 offset:8192
	ds_read_b64 v[64:65], v23 offset:12288
	ds_read_b64 v[66:67], v23 offset:16384
	ds_read_b64 v[68:69], v23 offset:20480
	ds_read_b64 v[70:71], v23 offset:24576
	ds_read_b64 v[72:73], v23 offset:28672
	v_and_b32_e32 v24, 15, v21
	v_lshrrev_b32_e32 v25, 4, v21
	v_lshlrev_b32_e32 v26, 4, v20
	v_lshl_add_u32 v26, v25, 2, v26
	v_lshl_add_u32 v26, v22, 1, v26
	s_lshl_b32 s6, s10, 4
	v_add_u32_e32 v24, s6, v24
	v_lshlrev_b32_e32 v24, 2, v24
	v_add_u32_e32 v28, 0x2000, v26
	v_mov_b32_e32 v29, 0
	v_lshlrev_b64 v[30:31], 14, v[28:29]
	v_mov_b32_e32 v25, 0
	v_lshl_add_u64 v[30:31], s[40:41], 0, v[30:31]
	v_lshl_add_u64 v[30:31], v[30:31], 0, v[24:25]
	global_load_dword v32, v[30:31], off
	s_movk_i32 s4, 0x4000
	s_mov_b32 s5, 0
	v_lshl_add_u64 v[38:39], v[30:31], 0, s[4:5]
	s_nop 0
	global_load_dword v33, v[38:39], off
	v_readlane_b32 s22, v254, 63
	v_readlane_b32 s30, v253, 56
	v_readlane_b32 s31, v253, 57
	v_add_u32_e32 v42, 0x1fc0, v26
	v_mov_b32_e32 v43, 0
	v_lshlrev_b64 v[34:35], 14, v[42:43]
	s_nop 2
	v_lshl_add_u64 v[34:35], s[30:31], 0, v[34:35]
	v_lshl_add_u64 v[34:35], v[34:35], 0, v[24:25]
	s_cmp_lg_u32 s22, 0
	s_cselect_b64 vcc, -1, 0
	v_cndmask_b32_e32 v36, v30, v34, vcc
	v_cndmask_b32_e32 v37, v31, v35, vcc
	s_waitcnt lgkmcnt(0)
	v_pk_add_f32 v[58:59], v[58:59], v[60:61]
	v_pk_add_f32 v[58:59], v[58:59], v[62:63]
	v_pk_add_f32 v[58:59], v[58:59], v[64:65]
	v_pk_add_f32 v[58:59], v[58:59], v[66:67]
	v_pk_add_f32 v[58:59], v[58:59], v[68:69]
	v_pk_add_f32 v[58:59], v[58:59], v[70:71]
	v_pk_add_f32 v[58:59], v[58:59], v[72:73]
	s_waitcnt vmcnt(0)
	v_add_f32_e32 v32, v32, v58
	v_add_f32_e32 v33, v33, v59
	global_store_dword v[36:37], v32, off
	v_lshl_add_u64 v[40:41], v[36:37], 0, s[4:5]
	s_nop 0
	global_store_dword v[40:41], v33, off
	v_readlane_b32 s16, v254, 60
	v_readlane_b32 s17, v254, 61
	s_branch .LBB0_1543
